# packed fp32 ops in the attention loops split into scalar pairs, on top of the V-load hoist
# baseline (speedup 1.0000x reference)
.LBB0_1187:
	s_or_b64 exec, exec, s[36:37]
	s_add_i32 s34, s34, 1
	s_bitcmp1_b32 s34, 0
	s_cselect_b32 s36, 0x3400, 0
	v_add_u32_e32 v112, s36, v180
	ds_read_b128 v[132:135], v112
	ds_read_b128 v[136:139], v112 offset:32
	v_exp_f32_e32 v174, v48
	v_exp_f32_e32 v175, v49
	v_exp_f32_e32 v182, v50
	s_waitcnt lgkmcnt(0)
	v_mfma_f32_32x32x16_bf16 v[80:95], v[132:135], v[100:103], v[32:47]
	v_exp_f32_e32 v183, v51
	v_exp_f32_e32 v184, v52
	v_exp_f32_e32 v185, v53
	v_exp_f32_e32 v186, v54
	v_exp_f32_e32 v187, v55
	v_exp_f32_e32 v188, v56
	v_exp_f32_e32 v189, v57
	v_mfma_f32_32x32x16_bf16 v[80:95], v[136:139], v[104:107], v[80:95]
	ds_read_b128 v[132:135], v112 offset:64
	ds_read_b128 v[136:139], v112 offset:96
	v_exp_f32_e32 v190, v58
	v_exp_f32_e32 v191, v59
	v_exp_f32_e32 v192, v60
	v_exp_f32_e32 v193, v61
	v_exp_f32_e32 v194, v62
	v_exp_f32_e32 v195, v63
	s_waitcnt lgkmcnt(0)
	v_mfma_f32_32x32x16_bf16 v[80:95], v[132:135], v[108:111], v[80:95]
	ds_read_b128 v[132:135], v112 offset:128
	ds_read_b128 v[48:51], v112 offset:160
	s_and_b64 s[18:19], s[18:19], exec
	s_cselect_b32 s18, 0x2400, 0
	v_exp_f32_e32 v198, v64
	v_exp_f32_e32 v199, v65
	v_exp_f32_e32 v200, v70
	v_mfma_f32_32x32x16_bf16 v[80:95], v[136:139], v[116:119], v[80:95]
	v_exp_f32_e32 v201, v71
	v_exp_f32_e32 v202, v72
	v_exp_f32_e32 v203, v73
	v_exp_f32_e32 v76, v76
	v_cvt_pk_bf16_f32 v71, v200, v201
	v_exp_f32_e32 v78, v78
	v_exp_f32_e32 v79, v79
	s_waitcnt lgkmcnt(0)
	v_mfma_f32_32x32x16_bf16 v[80:95], v[132:135], v[120:123], v[80:95]
	ds_read_b128 v[132:135], v112 offset:6656
	ds_read_b128 v[146:149], v112 offset:6688
	v_exp_f32_e32 v77, v77
	v_cmp_eq_u32_e32 vcc, s34, v173
	v_lshl_add_u64 v[142:143], v[142:143], 0, s[24:25]
	v_lshl_add_u64 v[162:163], v[162:163], 0, s[24:25]
	s_or_b64 s[2:3], vcc, s[2:3]
	v_mfma_f32_32x32x16_bf16 v[80:95], v[48:51], v[96:99], v[80:95]
	s_waitcnt lgkmcnt(0)
	v_mfma_f32_32x32x16_bf16 v[48:63], v[132:135], v[100:103], v[32:47]
	ds_read_b128 v[150:153], v112 offset:6720
	ds_read_b128 v[154:157], v112 offset:6752
	ds_read_b128 v[158:161], v112 offset:6784
	ds_read_b128 v[136:139], v112 offset:6816
	v_add_u32_e32 v112, s18, v179
	v_lshl_add_u64 v[164:165], v[164:165], 0, s[0:1]
	v_mfma_f32_32x32x16_bf16 v[48:63], v[146:149], v[104:107], v[48:63]
	v_exp_f32_e32 v146, v66
	v_exp_f32_e32 v147, v67
	v_exp_f32_e32 v148, v68
	v_exp_f32_e32 v149, v69
	ds_read_b64_tr_b16 v[64:65], v112 offset:26624
	ds_read_b64_tr_b16 v[66:67], v112 offset:27776
	v_cvt_pk_bf16_f32 v68, v198, v199
	v_cvt_pk_bf16_f32 v69, v146, v147
	s_waitcnt lgkmcnt(0)
	v_mfma_f32_32x32x16_bf16 v[48:63], v[150:153], v[108:111], v[48:63]
	v_exp_f32_e32 v150, v74
	v_exp_f32_e32 v151, v75
	ds_read_b64_tr_b16 v[74:75], v112 offset:27840
	ds_read_b64_tr_b16 v[72:73], v112 offset:26688
	v_cvt_pk_bf16_f32 v70, v148, v149
	v_add_f32_e32 v146, v182, v146
	v_add_f32_e32 v147, v183, v147
	v_add_f32_e32 v198, v174, v198
	v_add_f32_e32 v199, v175, v199
	v_add_f32_e32 v148, v184, v148
	v_add_f32_e32 v149, v185, v149
	v_mfma_f32_32x32x16_bf16 v[0:15], v[64:67], v[68:71], v[0:15]
	ds_read_b64_tr_b16 v[64:65], v112 offset:28928
	ds_read_b64_tr_b16 v[66:67], v112 offset:30080
	v_add_f32_e64 v152, v194, v78
	v_add_f32_e64 v153, v195, v79
	s_waitcnt lgkmcnt(0)
	v_mfma_f32_32x32x16_bf16 v[16:31], v[72:75], v[68:71], v[16:31]
	ds_read_b64_tr_b16 v[74:75], v112 offset:30144
	ds_read_b64_tr_b16 v[72:73], v112 offset:28992
	v_cvt_pk_bf16_f32 v68, v202, v203
	v_cvt_pk_bf16_f32 v69, v150, v151
	v_cvt_pk_bf16_f32 v70, v76, v77
	v_cvt_pk_bf16_f32 v71, v78, v79
	v_mfma_f32_32x32x16_bf16 v[48:63], v[154:157], v[116:119], v[48:63]
	v_add_f32_e64 v154, v192, v76
	v_add_f32_e64 v155, v193, v77
	v_add_f32_e64 v156, v190, v150
	v_add_f32_e64 v157, v191, v151
	v_mfma_f32_32x32x16_bf16 v[0:15], v[64:67], v[68:71], v[0:15]
	s_waitcnt lgkmcnt(0)
	v_mfma_f32_32x32x16_bf16 v[16:31], v[72:75], v[68:71], v[16:31]
	v_cvt_pk_bf16_f32 v68, v174, v175
	v_cvt_pk_bf16_f32 v69, v182, v183
	v_cvt_pk_bf16_f32 v70, v184, v185
	v_cvt_pk_bf16_f32 v71, v186, v187
	v_mfma_f32_32x32x16_bf16 v[48:63], v[158:161], v[120:123], v[48:63]
	v_add_f32_e64 v160, v186, v200
	v_add_f32_e64 v161, v187, v201
	v_mov_b32_e32 v200, v199
	v_mov_b32_e32 v201, v146
	v_mov_b32_e32 v199, v147
	v_add_f32_e32 v64, v200, v198
	v_add_f32_e32 v65, v201, v199
	v_mov_b32_e32 v78, v149
	v_mov_b32_e32 v79, v160
	v_add_f32_e32 v76, v64, v64
	v_add_f32_e32 v77, v64, v65
	ds_read_b64_tr_b16 v[64:65], v112 offset:31232
	ds_read_b64_tr_b16 v[66:67], v112 offset:32384
	ds_read_b64_tr_b16 v[74:75], v112 offset:32448
	ds_read_b64_tr_b16 v[72:73], v112 offset:31296
	s_waitcnt lgkmcnt(0)
	v_mfma_f32_32x32x16_bf16 v[0:15], v[64:67], v[68:71], v[0:15]
	ds_read_b64_tr_b16 v[64:65], v112 offset:33536
	ds_read_b64_tr_b16 v[66:67], v112 offset:34688
	v_mov_b32_e32 v149, v161
	v_add_f32_e64 v78, v78, v148
	v_add_f32_e64 v79, v79, v149
	v_add_f32_e32 v158, v188, v202
	v_add_f32_e32 v159, v189, v203
	v_add_f32_e32 v79, v78, v79
	v_add_f32_e32 v78, v78, v78
	v_add_f32_e32 v147, v158, v159
	v_add_f32_e32 v149, v156, v157
	v_mfma_f32_32x32x16_bf16 v[16:31], v[72:75], v[68:71], v[16:31]
	ds_read_b64_tr_b16 v[74:75], v112 offset:34752
	ds_read_b64_tr_b16 v[72:73], v112 offset:33600
	v_cvt_pk_bf16_f32 v68, v188, v189
	v_cvt_pk_bf16_f32 v69, v190, v191
	v_cvt_pk_bf16_f32 v70, v192, v193
	v_cvt_pk_bf16_f32 v71, v194, v195
	v_mov_b32_e32 v146, v154
	v_mov_b32_e32 v148, v155
	s_waitcnt lgkmcnt(0)
	v_mfma_f32_32x32x16_bf16 v[0:15], v[64:67], v[68:71], v[0:15]
	v_mov_b32_e32 v76, v152
	v_mov_b32_e32 v78, v153
	v_add_f32_e64 v146, v146, v148
	v_add_f32_e64 v147, v147, v149
	v_add_f32_e64 v64, v76, v78
	v_add_f32_e64 v65, v77, v79
	v_add_f32_e32 v64, v146, v64
	v_add_f32_e32 v65, v147, v65
	s_barrier
	v_mfma_f32_32x32x16_bf16 v[16:31], v[72:75], v[68:71], v[16:31]
	v_add_f32_e32 v64, v64, v65
	v_add_f32_e32 v114, v114, v64
	v_mov_b64_e32 v[64:65], v[80:81]
	v_mov_b64_e32 v[66:67], v[82:83]
	v_mov_b64_e32 v[68:69], v[84:85]
	v_mov_b64_e32 v[70:71], v[86:87]
	v_mov_b64_e32 v[72:73], v[88:89]
	v_mfma_f32_32x32x16_bf16 v[48:63], v[136:139], v[96:99], v[48:63]
	v_mov_b64_e32 v[74:75], v[90:91]
	v_mov_b64_e32 v[76:77], v[92:93]
	v_mov_b64_e32 v[78:79], v[94:95]
	s_andn2_b64 exec, exec, s[2:3]
	s_cbranch_execz .LBB0_1192
